# MLA loop unrolled by LDS parity on top of v36: 13 per-tile address adds folded into precomputed v213-224 + ds_read immediates (paired re-check; quick timings drift +-40us)
# baseline (speedup 1.0000x reference)
.LBB0_510:
	s_and_b64 vcc, exec, s[4:5]
	s_cbranch_vccz .LBB0_498
	s_lshl_b32 s0, s11, 2
	s_lshr_b32 s1, s18, 4
	s_lshr_b32 s4, s11, 1
	s_and_b32 s0, s0, 4
	v_readlane_b32 s16, v254, 44
	s_or_b32 s19, s1, s0
	s_lshl_b32 s0, s4, 12
	v_readlane_b32 s17, v254, 45
	s_mov_b32 s31, s17
	s_add_i32 s30, s0, 0x2000
	s_lshl_b32 s0, s18, 8
	s_and_b32 s29, s0, 0xf00
	s_lshl_b64 s[0:1], s[30:31], 3
	s_or_b32 s0, s0, s19
	s_mul_i32 s5, s0, 0x180
	s_mul_hi_u32 s0, s0, 0x180
	s_mulk_i32 s1, 0x180
	s_or_b32 s20, s29, s30
	s_add_i32 s0, s0, s1
	v_readlane_b32 s25, v254, 38
	s_add_u32 s16, s25, s5
	v_readlane_b32 s26, v254, 39
	s_addc_u32 s17, s26, s0
	s_lshl_b64 s[0:1], s[30:31], 12
	v_readlane_b32 s27, v254, 40
	s_add_u32 s0, s27, s0
	v_readlane_b32 s28, v254, 41
	s_addc_u32 s1, s28, s1
	s_lshl_b32 s21, s19, 7
	s_lshl_b32 s18, s19, 8
	s_add_u32 s0, s0, s18
	s_addc_u32 s1, s1, 0
	s_add_u32 s23, s0, 0x800
	s_addc_u32 s24, s1, 0
	s_lshl_b32 s4, s4, 9
	s_add_i32 s30, s4, 0x6000
	s_lshl_b64 s[4:5], s[30:31], 3
	s_or_b32 s4, s4, s19
	s_mul_i32 s22, s4, 0x180
	s_mul_hi_u32 s4, s4, 0x180
	s_mulk_i32 s5, 0x180
	s_add_i32 s4, s4, s5
	s_add_u32 s25, s25, s22
	s_addc_u32 s26, s26, s4
	s_lshl_b64 s[4:5], s[30:31], 12
	s_add_u32 s4, s27, s4
	s_addc_u32 s5, s28, s5
	s_add_u32 s4, s4, s18
	s_addc_u32 s5, s5, 0
	s_add_u32 s27, s4, 0x800
	s_addc_u32 s28, s5, 0
	s_mul_i32 s5, s20, 0x8200
	s_mul_hi_u32 s4, s20, 0x8200
	s_add_u32 s18, s39, s5
	v_readlane_b32 s5, v254, 24
	s_addc_u32 s22, s5, s4
	s_mov_b32 s5, s31
	s_mul_i32 s30, s19, 0xc0
	v_writelane_b32 v254, s4, 44
	v_mov_b32_e32 v201, v0
	v_mov_b32_e32 v13, v3
	v_writelane_b32 v254, s5, 45
	s_lshl_b64 s[4:5], s[30:31], 1
	s_add_u32 s18, s18, s4
	v_readfirstlane_b32 s4, v201
	s_addc_u32 s19, s22, s5
	s_ashr_i32 s5, s4, 6
	v_and_b32_e32 v149, 31, v201
	s_lshl_b32 s22, s5, 5
	v_bfe_u32 v1, v201, 5, 1
	v_or_b32_e32 v2, s22, v149
	v_mov_b64_e32 v[4:5], s[18:19]
	v_mad_i64_i32 v[4:5], s[18:19], v2, s36, v[4:5]
	v_lshlrev_b32_e32 v2, 4, v1
	v_lshl_add_u64 v[4:5], v[4:5], 0, v[2:3]
	global_load_dwordx4 v[128:131], v[4:5], off offset:320
	global_load_dwordx4 v[140:143], v[4:5], off offset:352
	global_load_dwordx4 v[164:167], v[4:5], off offset:256
	global_load_dwordx4 v[172:175], v[4:5], off offset:288
	global_load_dwordx4 v[116:119], v[4:5], off
	global_load_dwordx4 v[120:123], v[4:5], off offset:32
	global_load_dwordx4 v[220:223], v[4:5], off offset:64
	global_load_dwordx4 v[212:215], v[4:5], off offset:96
	global_load_dwordx4 v[182:185], v[4:5], off offset:224
	global_load_dwordx4 v[186:189], v[4:5], off offset:192
	global_load_dwordx4 v[204:207], v[4:5], off offset:128
	global_load_dwordx4 v[190:193], v[4:5], off offset:160
	v_or_b32_e32 v14, s29, v149
	v_and_b32_e32 v12, 32, v201
	v_add_u32_e32 v126, s22, v14
	global_load_dwordx4 v[112:115], v12, s[42:43]
	global_load_dwordx4 v[100:103], v12, s[42:43] offset:16
	global_load_dwordx4 v[108:111], v12, s[42:43] offset:64
	global_load_dwordx4 v[104:107], v12, s[42:43] offset:80
	global_load_dwordx4 v[96:99], v12, s[42:43] offset:128
	global_load_dwordx4 v[92:95], v12, s[42:43] offset:144
	global_load_dwordx4 v[88:91], v12, s[42:43] offset:192
	global_load_dwordx4 v[84:87], v12, s[42:43] offset:208
	global_load_dwordx4 v[80:83], v12, s[42:43] offset:256
	global_load_dwordx4 v[76:79], v12, s[42:43] offset:272
	global_load_dwordx4 v[72:75], v12, s[42:43] offset:320
	global_load_dwordx4 v[68:71], v12, s[42:43] offset:336
	global_load_dwordx4 v[64:67], v12, s[42:43] offset:384
	global_load_dwordx4 v[60:63], v12, s[42:43] offset:400
	global_load_dwordx4 v[8:11], v12, s[42:43] offset:448
	global_load_dwordx4 v[4:7], v12, s[42:43] offset:464
	global_load_dwordx4 v[56:59], v12, s[42:43] offset:512
	global_load_dwordx4 v[52:55], v12, s[42:43] offset:528
	global_load_dwordx4 v[48:51], v12, s[42:43] offset:576
	global_load_dwordx4 v[44:47], v12, s[42:43] offset:592
	global_load_dwordx4 v[40:43], v12, s[42:43] offset:640
	global_load_dwordx4 v[36:39], v12, s[42:43] offset:656
	global_load_dwordx4 v[24:27], v12, s[42:43] offset:704
	global_load_dwordx4 v[20:23], v12, s[42:43] offset:720
	v_lshl_add_u64 v[124:125], s[12:13], 0, v[12:13]
	v_lshl_add_u64 v[170:171], s[14:15], 0, v[12:13]
	v_ashrrev_i32_e32 v12, 2, v126
	v_and_b32_e32 v12, -16, v12
	v_ashrrev_i32_e32 v13, 31, v12
	v_lshlrev_b32_e32 v126, 6, v126
	v_lshlrev_b64 v[16:17], 2, v[12:13]
	v_and_b32_e32 v178, 0xfc0, v126
	v_mov_b32_e32 v179, v3
	v_lshl_add_u64 v[18:19], v[124:125], 0, v[16:17]
	v_lshl_add_u64 v[180:181], v[124:125], 0, v[178:179]
	v_lshl_add_u64 v[32:33], v[170:171], 0, v[16:17]
	global_load_dwordx4 v[12:15], v[18:19], off offset:16
	global_load_dwordx4 v[28:31], v[18:19], off
	s_nop 0
	global_load_dwordx4 v[16:19], v[32:33], off offset:16
	s_nop 0
	global_load_dwordx4 v[32:35], v[32:33], off
	s_lshl_b32 s18, s5, 12
	v_and_b32_e32 v202, 63, v201
	s_add_i32 s18, s18, 0
	s_add_i32 s18, s18, 0x14800
	v_lshlrev_b32_e32 v203, 4, v202
	v_add_u32_e32 v200, s18, v203
	s_lshl_b32 s5, s5, 10
	s_add_i32 s29, s5, 0
	s_movk_i32 s5, 0x600
	s_add_i32 m0, s29, 0x8000
	s_mov_b64 s[18:19], 0x800
	s_add_i32 s30, s29, 0x10000
	s_and_b32 s4, s4, 0x3fffffc0
	s_lshl_b32 s4, s4, 2
	s_add_i32 s4, s4, 0
	s_add_i32 s4, s4, 0x14000
	s_waitcnt vmcnt(35)
	v_lshlrev_b32_e32 v232, 16, v118
	s_waitcnt vmcnt(34)
	v_lshlrev_b32_e32 v224, 16, v122
	s_waitcnt vmcnt(33)
	v_lshlrev_b32_e32 v216, 16, v222
	v_lshlrev_b32_e32 v126, 16, v131
	v_and_b32_e32 v127, 0xffff0000, v131
	v_lshlrev_b32_e32 v124, 16, v143
	v_and_b32_e32 v125, 0xffff0000, v143
	v_lshlrev_b32_e32 v136, 16, v130
	v_and_b32_e32 v137, 0xffff0000, v130
	v_lshlrev_b32_e32 v134, 16, v142
	v_and_b32_e32 v135, 0xffff0000, v142
	v_lshlrev_b32_e32 v144, 16, v129
	v_and_b32_e32 v145, 0xffff0000, v129
	v_lshlrev_b32_e32 v138, 16, v141
	v_and_b32_e32 v139, 0xffff0000, v141
	v_lshlrev_b32_e32 v150, 16, v128
	v_and_b32_e32 v151, 0xffff0000, v128
	v_lshlrev_b32_e32 v146, 16, v140
	v_and_b32_e32 v147, 0xffff0000, v140
	v_lshlrev_b32_e32 v154, 16, v167
	v_and_b32_e32 v155, 0xffff0000, v167
	v_lshlrev_b32_e32 v152, 16, v175
	v_and_b32_e32 v153, 0xffff0000, v175
	v_lshlrev_b32_e32 v158, 16, v166
	v_and_b32_e32 v159, 0xffff0000, v166
	v_lshlrev_b32_e32 v156, 16, v174
	v_and_b32_e32 v157, 0xffff0000, v174
	v_lshlrev_b32_e32 v162, 16, v165
	v_and_b32_e32 v163, 0xffff0000, v165
	v_lshlrev_b32_e32 v160, 16, v173
	v_and_b32_e32 v161, 0xffff0000, v173
	v_lshlrev_b32_e32 v166, 16, v164
	v_and_b32_e32 v167, 0xffff0000, v164
	v_lshlrev_b32_e32 v164, 16, v172
	v_and_b32_e32 v165, 0xffff0000, v172
	s_waitcnt vmcnt(31)
	v_lshlrev_b32_e32 v128, 16, v185
	v_and_b32_e32 v129, 0xffff0000, v185
	v_lshlrev_b32_e32 v130, 16, v183
	v_and_b32_e32 v131, 0xffff0000, v183
	v_lshlrev_b32_e32 v140, 16, v184
	v_and_b32_e32 v141, 0xffff0000, v184
	v_lshlrev_b32_e32 v142, 16, v182
	v_and_b32_e32 v143, 0xffff0000, v182
	s_waitcnt vmcnt(30)
	v_lshlrev_b32_e32 v168, 16, v189
	v_and_b32_e32 v169, 0xffff0000, v189
	v_lshlrev_b32_e32 v172, 16, v187
	v_and_b32_e32 v173, 0xffff0000, v187
	v_lshlrev_b32_e32 v174, 16, v188
	v_and_b32_e32 v175, 0xffff0000, v188
	v_lshlrev_b32_e32 v176, 16, v186
	v_and_b32_e32 v177, 0xffff0000, v186
	s_waitcnt vmcnt(28)
	v_lshlrev_b32_e32 v182, 16, v193
	v_and_b32_e32 v183, 0xffff0000, v193
	v_lshlrev_b32_e32 v184, 16, v191
	v_and_b32_e32 v185, 0xffff0000, v191
	v_lshlrev_b32_e32 v186, 16, v192
	v_and_b32_e32 v187, 0xffff0000, v192
	v_lshlrev_b32_e32 v188, 16, v190
	v_and_b32_e32 v189, 0xffff0000, v190
	v_lshlrev_b32_e32 v190, 16, v207
	v_and_b32_e32 v191, 0xffff0000, v207
	v_lshlrev_b32_e32 v192, 16, v205
	v_and_b32_e32 v193, 0xffff0000, v205
	v_lshlrev_b32_e32 v194, 16, v206
	v_and_b32_e32 v195, 0xffff0000, v206
	v_lshlrev_b32_e32 v196, 16, v204
	v_and_b32_e32 v197, 0xffff0000, v204
	v_lshlrev_b32_e32 v204, 16, v215
	v_and_b32_e32 v205, 0xffff0000, v215
	v_lshlrev_b32_e32 v206, 16, v213
	v_and_b32_e32 v207, 0xffff0000, v213
	v_lshlrev_b32_e32 v208, 16, v214
	v_and_b32_e32 v209, 0xffff0000, v214
	v_lshlrev_b32_e32 v210, 16, v212
	v_and_b32_e32 v211, 0xffff0000, v212
	v_lshlrev_b32_e32 v212, 16, v223
	v_and_b32_e32 v213, 0xffff0000, v223
	v_lshlrev_b32_e32 v214, 16, v221
	v_and_b32_e32 v215, 0xffff0000, v221
	v_and_b32_e32 v217, 0xffff0000, v222
	v_lshlrev_b32_e32 v218, 16, v220
	v_and_b32_e32 v219, 0xffff0000, v220
	v_lshlrev_b32_e32 v220, 16, v123
	v_and_b32_e32 v221, 0xffff0000, v123
	v_lshlrev_b32_e32 v222, 16, v121
	v_and_b32_e32 v223, 0xffff0000, v121
	v_and_b32_e32 v225, 0xffff0000, v122
	v_lshlrev_b32_e32 v122, 16, v120
	v_and_b32_e32 v123, 0xffff0000, v120
	v_lshlrev_b32_e32 v120, 16, v119
	v_and_b32_e32 v121, 0xffff0000, v119
	v_and_b32_e32 v119, 0xffff0000, v116
	v_and_b32_e32 v233, 0xffff0000, v118
	v_lshlrev_b32_e32 v118, 16, v116
	v_mul_f32_e32 v116, v119, v119
	v_lshlrev_b32_e32 v230, 16, v117
	v_and_b32_e32 v231, 0xffff0000, v117
	v_pk_fma_f32 v[116:117], v[118:119], v[118:119], v[116:117] op_sel_hi:[1,1,0]
	v_mul_f32_e32 v226, v231, v231
	v_pk_fma_f32 v[116:117], v[230:231], v[230:231], v[116:117]
	s_nop 0
	v_pk_add_f32 v[116:117], v[226:227], v[116:117] op_sel_hi:[0,1]
	v_pk_fma_f32 v[116:117], v[232:233], v[232:233], v[116:117]
	v_mul_f32_e32 v226, v233, v233
	v_pk_add_f32 v[116:117], v[226:227], v[116:117] op_sel_hi:[0,1]
	v_pk_fma_f32 v[116:117], v[120:121], v[120:121], v[116:117]
	v_mul_f32_e32 v226, v121, v121
	v_pk_add_f32 v[116:117], v[226:227], v[116:117] op_sel_hi:[0,1]
	v_pk_fma_f32 v[116:117], v[122:123], v[122:123], v[116:117]
	v_mul_f32_e32 v226, v123, v123
	v_pk_add_f32 v[116:117], v[226:227], v[116:117] op_sel_hi:[0,1]
	v_pk_fma_f32 v[116:117], v[222:223], v[222:223], v[116:117]
	v_mul_f32_e32 v226, v223, v223
	v_pk_add_f32 v[116:117], v[226:227], v[116:117] op_sel_hi:[0,1]
	v_pk_fma_f32 v[116:117], v[224:225], v[224:225], v[116:117]
	v_mul_f32_e32 v226, v225, v225
	v_pk_add_f32 v[116:117], v[226:227], v[116:117] op_sel_hi:[0,1]
	v_pk_fma_f32 v[116:117], v[220:221], v[220:221], v[116:117]
	v_mul_f32_e32 v226, v221, v221
	v_pk_add_f32 v[116:117], v[226:227], v[116:117] op_sel_hi:[0,1]
	v_pk_fma_f32 v[116:117], v[218:219], v[218:219], v[116:117]
	v_mul_f32_e32 v226, v219, v219
	v_pk_add_f32 v[116:117], v[226:227], v[116:117] op_sel_hi:[0,1]
	v_pk_fma_f32 v[116:117], v[214:215], v[214:215], v[116:117]
	v_mul_f32_e32 v226, v215, v215
	v_pk_add_f32 v[116:117], v[226:227], v[116:117] op_sel_hi:[0,1]
	v_pk_fma_f32 v[116:117], v[216:217], v[216:217], v[116:117]
	v_mul_f32_e32 v226, v217, v217
	v_pk_add_f32 v[116:117], v[226:227], v[116:117] op_sel_hi:[0,1]
	v_pk_fma_f32 v[116:117], v[212:213], v[212:213], v[116:117]
	v_mul_f32_e32 v226, v213, v213
	v_pk_add_f32 v[116:117], v[226:227], v[116:117] op_sel_hi:[0,1]
	v_pk_fma_f32 v[116:117], v[210:211], v[210:211], v[116:117]
	v_mul_f32_e32 v226, v211, v211
	v_pk_add_f32 v[116:117], v[226:227], v[116:117] op_sel_hi:[0,1]
	v_pk_fma_f32 v[116:117], v[206:207], v[206:207], v[116:117]
	v_mul_f32_e32 v226, v207, v207
	v_pk_add_f32 v[116:117], v[226:227], v[116:117] op_sel_hi:[0,1]
	v_pk_fma_f32 v[116:117], v[208:209], v[208:209], v[116:117]
	v_mul_f32_e32 v226, v209, v209
	v_pk_add_f32 v[116:117], v[226:227], v[116:117] op_sel_hi:[0,1]
	v_pk_fma_f32 v[116:117], v[204:205], v[204:205], v[116:117]
	v_mul_f32_e32 v226, v205, v205
	v_pk_add_f32 v[116:117], v[226:227], v[116:117] op_sel_hi:[0,1]
	v_pk_fma_f32 v[116:117], v[196:197], v[196:197], v[116:117]
	v_mul_f32_e32 v226, v197, v197
	v_pk_add_f32 v[116:117], v[226:227], v[116:117] op_sel_hi:[0,1]
	v_pk_fma_f32 v[116:117], v[192:193], v[192:193], v[116:117]
	v_mul_f32_e32 v226, v193, v193
	v_pk_add_f32 v[116:117], v[226:227], v[116:117] op_sel_hi:[0,1]
	v_pk_fma_f32 v[116:117], v[194:195], v[194:195], v[116:117]
	v_mul_f32_e32 v226, v195, v195
	v_pk_add_f32 v[116:117], v[226:227], v[116:117] op_sel_hi:[0,1]
	v_pk_fma_f32 v[116:117], v[190:191], v[190:191], v[116:117]
	v_mul_f32_e32 v226, v191, v191
	v_pk_add_f32 v[116:117], v[226:227], v[116:117] op_sel_hi:[0,1]
	v_pk_fma_f32 v[116:117], v[188:189], v[188:189], v[116:117]
	v_mul_f32_e32 v226, v189, v189
	v_pk_add_f32 v[116:117], v[226:227], v[116:117] op_sel_hi:[0,1]
	v_pk_fma_f32 v[116:117], v[184:185], v[184:185], v[116:117]
	v_mul_f32_e32 v226, v185, v185
	v_pk_add_f32 v[116:117], v[226:227], v[116:117] op_sel_hi:[0,1]
	v_pk_fma_f32 v[116:117], v[186:187], v[186:187], v[116:117]
	v_mul_f32_e32 v226, v187, v187
	v_pk_add_f32 v[116:117], v[226:227], v[116:117] op_sel_hi:[0,1]
	v_pk_fma_f32 v[116:117], v[182:183], v[182:183], v[116:117]
	v_mul_f32_e32 v226, v183, v183
	v_pk_add_f32 v[116:117], v[226:227], v[116:117] op_sel_hi:[0,1]
	v_pk_fma_f32 v[116:117], v[176:177], v[176:177], v[116:117]
	v_mul_f32_e32 v226, v177, v177
	v_pk_add_f32 v[116:117], v[226:227], v[116:117] op_sel_hi:[0,1]
	v_pk_fma_f32 v[116:117], v[172:173], v[172:173], v[116:117]
	v_mul_f32_e32 v226, v173, v173
	v_pk_add_f32 v[116:117], v[226:227], v[116:117] op_sel_hi:[0,1]
	v_pk_fma_f32 v[116:117], v[174:175], v[174:175], v[116:117]
	v_mul_f32_e32 v226, v175, v175
	v_pk_add_f32 v[116:117], v[226:227], v[116:117] op_sel_hi:[0,1]
	v_pk_fma_f32 v[116:117], v[168:169], v[168:169], v[116:117]
	v_mul_f32_e32 v226, v169, v169
	v_pk_add_f32 v[116:117], v[226:227], v[116:117] op_sel_hi:[0,1]
	v_pk_fma_f32 v[116:117], v[142:143], v[142:143], v[116:117]
	v_mul_f32_e32 v226, v143, v143
	v_pk_add_f32 v[116:117], v[226:227], v[116:117] op_sel_hi:[0,1]
	v_pk_fma_f32 v[116:117], v[130:131], v[130:131], v[116:117]
	v_mul_f32_e32 v226, v131, v131
	v_pk_add_f32 v[116:117], v[226:227], v[116:117] op_sel_hi:[0,1]
	v_pk_fma_f32 v[116:117], v[140:141], v[140:141], v[116:117]
	v_mul_f32_e32 v226, v141, v141
	v_pk_add_f32 v[116:117], v[226:227], v[116:117] op_sel_hi:[0,1]
	v_pk_fma_f32 v[116:117], v[128:129], v[128:129], v[116:117]
	v_mul_f32_e32 v226, v129, v129
	v_pk_add_f32 v[116:117], v[226:227], v[116:117] op_sel_hi:[0,1]
	v_pk_fma_f32 v[116:117], v[166:167], v[166:167], v[116:117]
	v_mul_f32_e32 v226, v167, v167
	v_pk_add_f32 v[116:117], v[226:227], v[116:117] op_sel_hi:[0,1]
	v_pk_fma_f32 v[116:117], v[162:163], v[162:163], v[116:117]
	v_mul_f32_e32 v226, v163, v163
	v_pk_add_f32 v[116:117], v[226:227], v[116:117] op_sel_hi:[0,1]
	v_pk_fma_f32 v[116:117], v[158:159], v[158:159], v[116:117]
	v_mul_f32_e32 v226, v159, v159
	v_pk_add_f32 v[116:117], v[226:227], v[116:117] op_sel_hi:[0,1]
	v_pk_fma_f32 v[116:117], v[154:155], v[154:155], v[116:117]
	v_mul_f32_e32 v226, v155, v155
	v_pk_add_f32 v[116:117], v[226:227], v[116:117] op_sel_hi:[0,1]
	v_pk_fma_f32 v[116:117], v[164:165], v[164:165], v[116:117]
	v_mul_f32_e32 v226, v165, v165
	v_pk_add_f32 v[116:117], v[226:227], v[116:117] op_sel_hi:[0,1]
	v_pk_fma_f32 v[116:117], v[160:161], v[160:161], v[116:117]
	v_mul_f32_e32 v226, v161, v161
	v_pk_add_f32 v[116:117], v[226:227], v[116:117] op_sel_hi:[0,1]
	v_pk_fma_f32 v[116:117], v[156:157], v[156:157], v[116:117]
	v_mul_f32_e32 v226, v157, v157
	v_pk_add_f32 v[116:117], v[226:227], v[116:117] op_sel_hi:[0,1]
	v_pk_fma_f32 v[116:117], v[152:153], v[152:153], v[116:117]
	v_mul_f32_e32 v226, v153, v153
	v_pk_add_f32 v[116:117], v[226:227], v[116:117] op_sel_hi:[0,1]
	v_pk_fma_f32 v[116:117], v[150:151], v[150:151], v[116:117]
	v_mul_f32_e32 v226, v151, v151
	v_pk_add_f32 v[116:117], v[226:227], v[116:117] op_sel_hi:[0,1]
	v_pk_fma_f32 v[116:117], v[144:145], v[144:145], v[116:117]
	v_mul_f32_e32 v226, v145, v145
	v_pk_add_f32 v[116:117], v[226:227], v[116:117] op_sel_hi:[0,1]
	v_pk_fma_f32 v[116:117], v[136:137], v[136:137], v[116:117]
	v_mul_f32_e32 v226, v137, v137
	v_pk_add_f32 v[116:117], v[226:227], v[116:117] op_sel_hi:[0,1]
	v_pk_fma_f32 v[116:117], v[126:127], v[126:127], v[116:117]
	v_mul_f32_e32 v226, v127, v127
	v_pk_add_f32 v[116:117], v[226:227], v[116:117] op_sel_hi:[0,1]
	v_pk_fma_f32 v[116:117], v[146:147], v[146:147], v[116:117]
	v_mul_f32_e32 v226, v147, v147
	v_pk_add_f32 v[116:117], v[226:227], v[116:117] op_sel_hi:[0,1]
	v_pk_fma_f32 v[116:117], v[138:139], v[138:139], v[116:117]
	v_mul_f32_e32 v226, v139, v139
	v_pk_add_f32 v[116:117], v[226:227], v[116:117] op_sel_hi:[0,1]
	v_pk_fma_f32 v[116:117], v[134:135], v[134:135], v[116:117]
	v_mul_f32_e32 v226, v135, v135
	v_pk_add_f32 v[116:117], v[226:227], v[116:117] op_sel_hi:[0,1]
	v_pk_fma_f32 v[116:117], v[124:125], v[124:125], v[116:117]
	v_mul_f32_e32 v226, v125, v125
	v_pk_add_f32 v[116:117], v[226:227], v[116:117] op_sel_hi:[0,1]
	v_mov_b32_e32 v117, v116
	s_nop 1
	v_permlane32_swap_b32_e32 v116, v117
	v_add_f32_e32 v116, v116, v117
	v_fmamk_f32 v116, v116, 0x3baaaaab, v198
	v_mul_f32_e32 v117, 0x4b800000, v116
	v_cmp_gt_f32_e32 vcc, s38, v116
	s_nop 1
	v_cndmask_b32_e32 v116, v116, v117, vcc
	v_rsq_f32_e32 v234, v116
	v_lshl_add_u64 v[116:117], v[170:171], 0, v[178:179]
	global_load_dwordx4 v[226:229], v[180:181], off offset:16
	s_nop 0
	global_load_dwordx4 v[178:181], v[180:181], off
	v_mul_f32_e32 v170, 0x45800000, v234
	v_cndmask_b32_e32 v170, v234, v170, vcc
	v_pk_mul_f32 v[118:119], v[170:171], v[118:119] op_sel_hi:[0,1]
	s_waitcnt vmcnt(29)
	v_pk_mul_f32 v[112:113], v[112:113], v[118:119]
	v_pk_mul_f32 v[118:119], v[170:171], v[230:231] op_sel_hi:[0,1]
	v_pk_mul_f32 v[114:115], v[114:115], v[118:119]
	v_pk_mul_f32 v[118:119], v[170:171], v[232:233] op_sel_hi:[0,1]
	global_load_dwordx4 v[230:233], v[116:117], off offset:16
	global_load_dwordx4 v[240:243], v[116:117], off
	s_waitcnt vmcnt(30)
	v_pk_mul_f32 v[118:119], v[100:101], v[118:119]
	v_pk_mul_f32 v[100:101], v[170:171], v[120:121] op_sel_hi:[0,1]
	v_pk_mul_f32 v[120:121], v[102:103], v[100:101]
	v_cvt_pk_bf16_f32 v100, v112, v113
	v_pk_mul_f32 v[112:113], v[170:171], v[122:123] op_sel_hi:[0,1]
	s_waitcnt vmcnt(29)
	v_pk_mul_f32 v[108:109], v[108:109], v[112:113]
	v_pk_mul_f32 v[112:113], v[170:171], v[224:225] op_sel_hi:[0,1]
	s_waitcnt vmcnt(28)
	v_pk_mul_f32 v[112:113], v[104:105], v[112:113]
	v_pk_mul_f32 v[104:105], v[170:171], v[222:223] op_sel_hi:[0,1]
	v_pk_mul_f32 v[110:111], v[110:111], v[104:105]
	v_pk_mul_f32 v[104:105], v[170:171], v[220:221] op_sel_hi:[0,1]
	v_cvt_pk_bf16_f32 v101, v114, v115
	v_pk_mul_f32 v[114:115], v[106:107], v[104:105]
	v_cvt_pk_bf16_f32 v104, v108, v109
	v_pk_mul_f32 v[108:109], v[170:171], v[218:219] op_sel_hi:[0,1]
	s_waitcnt vmcnt(27)
	v_pk_mul_f32 v[96:97], v[96:97], v[108:109]
	v_pk_mul_f32 v[108:109], v[170:171], v[216:217] op_sel_hi:[0,1]
	s_waitcnt vmcnt(26)
	v_pk_mul_f32 v[92:93], v[92:93], v[108:109]
	v_cvt_pk_bf16_f32 v105, v110, v111
	v_cvt_pk_bf16_f32 v110, v92, v93
	v_pk_mul_f32 v[92:93], v[170:171], v[210:211] op_sel_hi:[0,1]
	s_waitcnt vmcnt(25)
	v_pk_mul_f32 v[88:89], v[88:89], v[92:93]
	v_pk_mul_f32 v[92:93], v[170:171], v[208:209] op_sel_hi:[0,1]
	s_waitcnt vmcnt(24)
	v_pk_mul_f32 v[84:85], v[84:85], v[92:93]
	v_cvt_pk_bf16_f32 v107, v114, v115
	v_cvt_pk_bf16_f32 v114, v84, v85
	v_pk_mul_f32 v[84:85], v[170:171], v[196:197] op_sel_hi:[0,1]
	s_waitcnt vmcnt(23)
	v_pk_mul_f32 v[80:81], v[80:81], v[84:85]
	v_pk_mul_f32 v[84:85], v[170:171], v[194:195] op_sel_hi:[0,1]
	s_waitcnt vmcnt(22)
	v_pk_mul_f32 v[76:77], v[76:77], v[84:85]
	v_cvt_pk_bf16_f32 v102, v118, v119
	v_cvt_pk_bf16_f32 v118, v76, v77
	v_pk_mul_f32 v[76:77], v[170:171], v[188:189] op_sel_hi:[0,1]
	s_waitcnt vmcnt(21)
	v_pk_mul_f32 v[72:73], v[76:77], v[72:73]
	v_pk_mul_f32 v[76:77], v[170:171], v[186:187] op_sel_hi:[0,1]
	s_waitcnt vmcnt(20)
	v_pk_mul_f32 v[68:69], v[76:77], v[68:69]
	v_pk_mul_f32 v[108:109], v[170:171], v[214:215] op_sel_hi:[0,1]
	v_cvt_pk_bf16_f32 v122, v68, v69
	v_pk_mul_f32 v[68:69], v[170:171], v[176:177] op_sel_hi:[0,1]
	s_waitcnt vmcnt(19)
	v_pk_mul_f32 v[64:65], v[68:69], v[64:65]
	v_pk_mul_f32 v[68:69], v[170:171], v[174:175] op_sel_hi:[0,1]
	s_waitcnt vmcnt(18)
	v_pk_mul_f32 v[60:61], v[68:69], v[60:61]
	v_pk_mul_f32 v[68:69], v[170:171], v[172:173] op_sel_hi:[0,1]
	v_pk_mul_f32 v[66:67], v[68:69], v[66:67]
	v_pk_mul_f32 v[68:69], v[170:171], v[168:169] op_sel_hi:[0,1]
	v_pk_mul_f32 v[62:63], v[68:69], v[62:63]
	v_pk_mul_f32 v[68:69], v[170:171], v[166:167] op_sel_hi:[0,1]
	s_waitcnt vmcnt(15)
	v_pk_mul_f32 v[56:57], v[68:69], v[56:57]
	v_pk_mul_f32 v[68:69], v[170:171], v[158:159] op_sel_hi:[0,1]
	s_waitcnt vmcnt(14)
	v_pk_mul_f32 v[52:53], v[68:69], v[52:53]
	v_pk_mul_f32 v[68:69], v[170:171], v[162:163] op_sel_hi:[0,1]
	v_pk_mul_f32 v[58:59], v[68:69], v[58:59]
	v_pk_mul_f32 v[68:69], v[170:171], v[154:155] op_sel_hi:[0,1]
	v_pk_mul_f32 v[54:55], v[68:69], v[54:55]
	v_pk_mul_f32 v[68:69], v[170:171], v[164:165] op_sel_hi:[0,1]
	s_waitcnt vmcnt(13)
	v_pk_mul_f32 v[48:49], v[68:69], v[48:49]
	v_pk_mul_f32 v[68:69], v[170:171], v[156:157] op_sel_hi:[0,1]
	s_waitcnt vmcnt(12)
	v_pk_mul_f32 v[44:45], v[68:69], v[44:45]
	v_pk_mul_f32 v[68:69], v[170:171], v[160:161] op_sel_hi:[0,1]
	v_pk_mul_f32 v[50:51], v[68:69], v[50:51]
	v_pk_mul_f32 v[68:69], v[170:171], v[152:153] op_sel_hi:[0,1]
	v_pk_mul_f32 v[46:47], v[68:69], v[46:47]
	v_pk_mul_f32 v[68:69], v[170:171], v[150:151] op_sel_hi:[0,1]
	s_waitcnt vmcnt(11)
	v_pk_mul_f32 v[40:41], v[68:69], v[40:41]
	v_pk_mul_f32 v[68:69], v[170:171], v[136:137] op_sel_hi:[0,1]
	s_waitcnt vmcnt(10)
	v_pk_mul_f32 v[36:37], v[68:69], v[36:37]
	v_pk_mul_f32 v[68:69], v[170:171], v[144:145] op_sel_hi:[0,1]
	v_pk_mul_f32 v[42:43], v[68:69], v[42:43]
	v_pk_mul_f32 v[68:69], v[170:171], v[126:127] op_sel_hi:[0,1]
	v_pk_mul_f32 v[38:39], v[68:69], v[38:39]
	v_pk_mul_f32 v[68:69], v[170:171], v[146:147] op_sel_hi:[0,1]
	s_waitcnt vmcnt(9)
	v_pk_mul_f32 v[24:25], v[68:69], v[24:25]
	v_pk_mul_f32 v[68:69], v[170:171], v[134:135] op_sel_hi:[0,1]
	s_waitcnt vmcnt(8)
	v_pk_mul_f32 v[20:21], v[68:69], v[20:21]
	v_pk_mul_f32 v[68:69], v[170:171], v[138:139] op_sel_hi:[0,1]
	v_pk_mul_f32 v[26:27], v[68:69], v[26:27]
	v_pk_mul_f32 v[68:69], v[170:171], v[124:125] op_sel_hi:[0,1]
	v_pk_mul_f32 v[22:23], v[68:69], v[22:23]
	s_waitcnt vmcnt(4)
	v_pk_mul_f32 v[68:69], v[56:57], v[32:33]
	v_pk_mul_f32 v[32:33], v[48:49], v[32:33]
	v_pk_fma_f32 v[68:69], v[48:49], v[28:29], v[68:69]
	v_pk_fma_f32 v[28:29], v[56:57], v[28:29], v[32:33] neg_lo:[0,0,1] neg_hi:[0,0,1]
	v_pk_mul_f32 v[32:33], v[58:59], v[34:35]
	v_pk_mul_f32 v[34:35], v[50:51], v[34:35]
	v_pk_fma_f32 v[32:33], v[50:51], v[30:31], v[32:33]
	v_pk_fma_f32 v[30:31], v[58:59], v[30:31], v[34:35] neg_lo:[0,0,1] neg_hi:[0,0,1]
	v_pk_mul_f32 v[34:35], v[52:53], v[16:17]
	v_pk_mul_f32 v[16:17], v[44:45], v[16:17]
	v_pk_fma_f32 v[34:35], v[44:45], v[12:13], v[34:35]
	v_pk_fma_f32 v[16:17], v[52:53], v[12:13], v[16:17] neg_lo:[0,0,1] neg_hi:[0,0,1]
	v_pk_mul_f32 v[12:13], v[54:55], v[18:19]
	v_pk_mul_f32 v[92:93], v[170:171], v[206:207] op_sel_hi:[0,1]
	v_pk_fma_f32 v[44:45], v[46:47], v[14:15], v[12:13]
	v_pk_mul_f32 v[12:13], v[46:47], v[18:19]
	v_pk_mul_f32 v[84:85], v[170:171], v[192:193] op_sel_hi:[0,1]
	v_pk_fma_f32 v[18:19], v[54:55], v[14:15], v[12:13] neg_lo:[0,0,1] neg_hi:[0,0,1]
	s_waitcnt vmcnt(0)
	v_pk_mul_f32 v[12:13], v[40:41], v[240:241]
	v_cvt_pk_bf16_f32 v14, v16, v17
	v_pk_fma_f32 v[46:47], v[24:25], v[178:179], v[12:13]
	v_pk_mul_f32 v[12:13], v[24:25], v[240:241]
	v_cvt_pk_bf16_f32 v15, v18, v19
	v_pk_fma_f32 v[24:25], v[40:41], v[178:179], v[12:13] neg_lo:[0,0,1] neg_hi:[0,0,1]
	v_pk_mul_f32 v[12:13], v[42:43], v[242:243]
	v_lshlrev_b32_e32 v19, 3, v201
	v_pk_fma_f32 v[40:41], v[26:27], v[180:181], v[12:13]
	v_pk_mul_f32 v[12:13], v[26:27], v[242:243]
	v_pk_mul_f32 v[76:77], v[170:171], v[184:185] op_sel_hi:[0,1]
	v_pk_fma_f32 v[26:27], v[42:43], v[180:181], v[12:13] neg_lo:[0,0,1] neg_hi:[0,0,1]
	v_pk_mul_f32 v[12:13], v[36:37], v[230:231]
	v_add_u32_e32 v154, s4, v2
	v_pk_fma_f32 v[42:43], v[20:21], v[226:227], v[12:13]
	v_pk_mul_f32 v[12:13], v[20:21], v[230:231]
	v_pk_mul_f32 v[98:99], v[98:99], v[108:109]
	v_pk_fma_f32 v[20:21], v[36:37], v[226:227], v[12:13] neg_lo:[0,0,1] neg_hi:[0,0,1]
	v_pk_mul_f32 v[12:13], v[38:39], v[232:233]
	v_pk_mul_f32 v[108:109], v[170:171], v[212:213] op_sel_hi:[0,1]
	v_pk_fma_f32 v[36:37], v[22:23], v[228:229], v[12:13]
	v_pk_mul_f32 v[12:13], v[22:23], v[232:233]
	v_pk_mul_f32 v[90:91], v[90:91], v[92:93]
	v_pk_fma_f32 v[22:23], v[38:39], v[228:229], v[12:13] neg_lo:[0,0,1] neg_hi:[0,0,1]
	v_cvt_pk_bf16_f32 v12, v28, v29
	v_cvt_pk_bf16_f32 v13, v30, v31
	ds_write_b128 v200, v[12:15]
	v_cvt_pk_bf16_f32 v12, v68, v69
	v_cvt_pk_bf16_f32 v13, v32, v33
	v_cvt_pk_bf16_f32 v14, v34, v35
	v_cvt_pk_bf16_f32 v15, v44, v45
	ds_write_b128 v200, v[12:15] offset:1024
	v_cvt_pk_bf16_f32 v12, v24, v25
	v_cvt_pk_bf16_f32 v13, v26, v27
	v_cvt_pk_bf16_f32 v14, v20, v21
	v_cvt_pk_bf16_f32 v15, v22, v23
	ds_write_b128 v200, v[12:15] offset:2048
	v_cvt_pk_bf16_f32 v12, v46, v47
	v_cvt_pk_bf16_f32 v13, v40, v41
	v_cvt_pk_bf16_f32 v14, v42, v43
	v_cvt_pk_bf16_f32 v15, v36, v37
	ds_write_b128 v200, v[12:15] offset:3072
	v_bfe_u32 v12, v201, 2, 2
	v_lshrrev_b32_e32 v14, 1, v201
	v_ashrrev_i32_e32 v15, 4, v201
	v_and_or_b32 v14, v14, 8, v12
	v_and_b32_e32 v12, 0x60, v201
	v_lshrrev_b32_e32 v16, 1, v15
	v_and_or_b32 v18, v19, 24, v12
	v_and_b32_e32 v12, -16, v15
	v_and_b32_e32 v16, 4, v16
	v_or3_b32 v12, v16, v12, v14
	v_add_u32_e32 v16, 0x200, v201
	v_ashrrev_i32_e32 v24, 4, v16
	v_and_b32_e32 v13, 15, v201
	v_lshrrev_b32_e32 v16, 1, v24
	v_bitop3_b32 v21, v15, v13, 7 bitop3:0x6c
	v_bitop3_b32 v26, v24, v13, 7 bitop3:0x6c
	v_and_b32_e32 v13, -16, v24
	v_and_b32_e32 v16, 4, v16
	v_ashrrev_i32_e32 v27, 3, v201
	v_mul_i32_i24_sdwa v134, sext(v15), s5 dst_sel:DWORD dst_unused:UNUSED_PAD src0_sel:WORD_0 src1_sel:DWORD
	v_or3_b32 v14, v16, v13, v14
	v_xor_b32_e32 v13, v27, v201
	v_ashrrev_i32_e32 v135, 31, v134
	v_lshlrev_b32_e32 v13, 3, v13
	v_lshl_add_u64 v[16:17], v[134:135], 1, s[16:17]
	v_lshlrev_b32_e32 v22, 4, v21
	v_mov_b32_e32 v23, v3
	v_and_b32_e32 v20, 56, v13
	v_lshl_add_u64 v[16:17], v[16:17], 0, v[22:23]
	v_ashrrev_i32_e32 v13, 31, v12
	global_load_lds_dwordx4 v[16:17], off
	v_lshlrev_b64 v[16:17], 12, v[12:13]
	v_lshl_add_u64 v[16:17], s[0:1], 0, v[16:17]
	v_lshlrev_b32_e32 v22, 1, v18
	v_lshl_add_u64 v[16:17], v[16:17], 0, v[22:23]
	v_mul_i32_i24_sdwa v136, sext(v24), s5 dst_sel:DWORD dst_unused:UNUSED_PAD src0_sel:WORD_0 src1_sel:DWORD
	v_lshl_add_u64 v[16:17], v[16:17], 0, s[18:19]
	s_mov_b32 m0, s29
	v_ashrrev_i32_e32 v137, 31, v136
	global_load_lds_dwordx4 v[16:17], off
	v_lshl_add_u64 v[16:17], v[136:137], 1, s[16:17]
	v_lshlrev_b32_e32 v24, 4, v26
	v_mov_b32_e32 v25, v3
	v_lshl_add_u64 v[16:17], v[16:17], 0, v[24:25]
	s_add_i32 m0, s29, 0xa000
	v_ashrrev_i32_e32 v15, 31, v14
	global_load_lds_dwordx4 v[16:17], off
	v_lshlrev_b64 v[16:17], 12, v[14:15]
	v_lshl_add_u64 v[16:17], s[0:1], 0, v[16:17]
	v_lshl_add_u64 v[16:17], v[16:17], 0, v[22:23]
	v_mul_i32_i24_sdwa v138, sext(v27), s5 dst_sel:DWORD dst_unused:UNUSED_PAD src0_sel:WORD_0 src1_sel:DWORD
	v_lshl_add_u64 v[16:17], v[16:17], 0, s[18:19]
	s_add_i32 m0, s29, 0x2000
	v_ashrrev_i32_e32 v139, 31, v138
	global_load_lds_dwordx4 v[16:17], off
	v_lshl_add_u64 v[16:17], v[138:139], 1, s[16:17]
	v_lshlrev_b32_e32 v22, 1, v20
	v_lshl_add_u64 v[16:17], v[16:17], 0, v[22:23]
	s_mov_b64 s[0:1], 0x100
	v_lshl_add_u64 v[16:17], v[16:17], 0, s[0:1]
	s_mov_b32 m0, s30
	v_lshlrev_b32_e32 v22, 3, v21
	global_load_lds_dwordx4 v[16:17], off
	v_pk_mul_f32 v[16:17], v[170:171], v[142:143] op_sel_hi:[0,1]
	v_pk_mul_f32 v[8:9], v[16:17], v[8:9]
	v_pk_mul_f32 v[16:17], v[170:171], v[140:141] op_sel_hi:[0,1]
	v_pk_mul_f32 v[4:5], v[16:17], v[4:5]
	v_pk_mul_f32 v[16:17], v[170:171], v[130:131] op_sel_hi:[0,1]
	v_pk_mul_f32 v[10:11], v[16:17], v[10:11]
	v_pk_mul_f32 v[16:17], v[170:171], v[128:129] op_sel_hi:[0,1]
	v_pk_mul_f32 v[6:7], v[16:17], v[6:7]
	v_cvt_pk_bf16_f32 v130, v4, v5
	v_cvt_pk_bf16_f32 v131, v6, v7
	v_lshlrev_b32_e32 v4, 1, v201
	v_lshlrev_b32_e32 v6, 4, v201
	v_and_b32_e32 v4, 32, v4
	v_and_b32_e32 v7, 0x70, v6
	v_lshlrev_b32_e32 v24, 3, v26
	v_and_b32_e32 v5, 0xc0, v203
	v_bitop3_b32 v156, v2, v6, s89 bitop3:0x78
	v_bitop3_b32 v157, v2, v7, 32 bitop3:0x36
	v_bitop3_b32 v158, v2, v7, 64 bitop3:0x36
	v_bitop3_b32 v160, v2, v7, s83 bitop3:0x36
	v_bitop3_b32 v161, v2, v7, s86 bitop3:0x36
	v_bitop3_b32 v162, v2, v7, s88 bitop3:0x36
	v_bitop3_b32 v163, v2, v7, s87 bitop3:0x36
	v_bitop3_b32 v164, v2, v7, s90 bitop3:0x36
	v_and_or_b32 v2, v19, s91, v4
	v_mov_b32_e32 v16, v3
	v_mov_b32_e32 v17, v3
	v_pk_mul_f32 v[92:93], v[170:171], v[204:205] op_sel_hi:[0,1]
	v_pk_mul_f32 v[82:83], v[82:83], v[84:85]
	v_pk_mul_f32 v[84:85], v[170:171], v[190:191] op_sel_hi:[0,1]
	v_pk_mul_f32 v[74:75], v[76:77], v[74:75]
	v_pk_mul_f32 v[76:77], v[170:171], v[182:183] op_sel_hi:[0,1]
	v_cvt_pk_bf16_f32 v124, v64, v65
	v_cvt_pk_bf16_f32 v125, v66, v67
	v_cvt_pk_bf16_f32 v126, v60, v61
	v_cvt_pk_bf16_f32 v127, v62, v63
	v_cvt_pk_bf16_f32 v128, v8, v9
	v_cvt_pk_bf16_f32 v129, v10, v11
	v_lshlrev_b64 v[140:141], 11, v[12:13]
	v_lshlrev_b64 v[142:143], 11, v[14:15]
	s_waitcnt vmcnt(0)
	v_add3_u32 v166, v5, 0, v2
	v_mov_b32_e32 v2, v3
	v_mov_b32_e32 v4, v3
	v_mov_b32_e32 v5, v3
	v_mov_b32_e32 v6, v3
	v_mov_b32_e32 v7, v3
	v_mov_b32_e32 v8, v3
	v_mov_b32_e32 v9, v3
	v_mov_b32_e32 v10, v3
	v_mov_b32_e32 v11, v3
	v_mov_b32_e32 v12, v3
	v_mov_b32_e32 v13, v3
	v_mov_b32_e32 v14, v3
	v_mov_b32_e32 v15, v3
	v_lshlrev_b32_e32 v144, 1, v22
	v_lshlrev_b32_e32 v150, 1, v24
	v_lshlrev_b32_e32 v152, 1, v20
	v_mov_b64_e32 v[66:67], v[16:17]
	v_mov_b64_e32 v[50:51], v[16:17]
	v_mov_b64_e32 v[34:35], v[16:17]
	v_pk_mul_f32 v[94:95], v[94:95], v[108:109]
	v_pk_mul_f32 v[86:87], v[86:87], v[92:93]
	v_pk_mul_f32 v[78:79], v[78:79], v[84:85]
	v_pk_mul_f32 v[70:71], v[76:77], v[70:71]
	v_lshlrev_b32_e32 v146, 1, v18
	v_mov_b64_e32 v[64:65], v[14:15]
	v_mov_b64_e32 v[62:63], v[12:13]
	v_mov_b64_e32 v[60:61], v[10:11]
	v_mov_b64_e32 v[58:59], v[8:9]
	v_mov_b64_e32 v[56:57], v[6:7]
	v_mov_b64_e32 v[54:55], v[4:5]
	v_mov_b64_e32 v[52:53], v[2:3]
	v_mov_b64_e32 v[48:49], v[14:15]
	v_mov_b64_e32 v[46:47], v[12:13]
	v_mov_b64_e32 v[44:45], v[10:11]
	v_mov_b64_e32 v[42:43], v[8:9]
	v_mov_b64_e32 v[40:41], v[6:7]
	v_mov_b64_e32 v[38:39], v[4:5]
	v_mov_b64_e32 v[36:37], v[2:3]
	v_mov_b64_e32 v[32:33], v[14:15]
	v_mov_b64_e32 v[30:31], v[12:13]
	v_mov_b64_e32 v[28:29], v[10:11]
	v_mov_b64_e32 v[26:27], v[8:9]
	v_mov_b64_e32 v[24:25], v[6:7]
	v_mov_b64_e32 v[22:23], v[4:5]
	v_mov_b64_e32 v[20:21], v[2:3]
	v_mov_b64_e32 v[18:19], v[16:17]
	v_cvt_pk_bf16_f32 v103, v120, v121
	v_cvt_pk_bf16_f32 v106, v112, v113
	v_cvt_pk_bf16_f32 v108, v96, v97
	v_cvt_pk_bf16_f32 v109, v98, v99
	v_cvt_pk_bf16_f32 v111, v94, v95
	v_cvt_pk_bf16_f32 v112, v88, v89
	v_cvt_pk_bf16_f32 v113, v90, v91
	v_cvt_pk_bf16_f32 v115, v86, v87
	v_cvt_pk_bf16_f32 v116, v80, v81
	v_cvt_pk_bf16_f32 v117, v82, v83
	v_cvt_pk_bf16_f32 v119, v78, v79
	v_cvt_pk_bf16_f32 v120, v72, v73
	v_cvt_pk_bf16_f32 v121, v74, v75
	v_cvt_pk_bf16_f32 v123, v70, v71
	v_lshlrev_b32_e32 v155, 8, v149
	v_lshlrev_b32_e32 v165, 7, v149
	v_cmp_gt_u32_e64 s[0:1], 32, v202
	v_lshl_add_u32 v159, v149, 2, s4
	s_mov_b32 s19, 0
	v_mov_b32_e32 v168, 0
	v_mov_b32_e32 v167, 0xf149f2ca
	v_mov_b64_e32 v[16:17], v[14:15]
	v_mov_b64_e32 v[14:15], v[12:13]
	v_mov_b64_e32 v[12:13], v[10:11]
	v_mov_b64_e32 v[10:11], v[8:9]
	v_mov_b64_e32 v[8:9], v[6:7]
	v_mov_b64_e32 v[6:7], v[4:5]
	v_mov_b64_e32 v[4:5], v[2:3]
	s_waitcnt vmcnt(0) lgkmcnt(0)
	s_barrier
	ds_read_b128 v[186:189], v200
	ds_read_b128 v[190:193], v200 offset:1024
	ds_read_b128 v[194:197], v200 offset:2048
	ds_read_b128 v[204:207], v200 offset:3072
	s_waitcnt lgkmcnt(0)
	v_lshl_add_u32 v208, v134, 1, v144
	v_lshl_add_u32 v209, v140, 1, v146
	v_lshl_add_u32 v210, v136, 1, v150
	v_lshl_add_u32 v211, v142, 1, v146
	v_lshl_add_u32 v212, v138, 1, v152
	v_add_u32_e32 v212, 0x100, v212
	v_add_u32_e32 v213, v156, v155
	v_add_u32_e32 v214, v157, v155
	v_add_u32_e32 v215, v158, v155
	v_add_u32_e32 v216, v160, v155
	v_add_u32_e32 v217, v161, v155
	v_add_u32_e32 v218, v162, v155
	v_add_u32_e32 v219, v163, v155
	v_add_u32_e32 v220, v164, v155
	s_mov_b32 s101, 0x10000
	v_add3_u32 v221, v156, v165, s101
	v_add3_u32 v222, v157, v165, s101
	v_add3_u32 v223, v158, v165, s101
	v_add3_u32 v224, v160, v165, s101
	s_and_b32 s18, s19, 1
	s_cmpk_lt_u32 s19, 0x47
	s_mov_b64 s[4:5], -1
	s_cbranch_scc1 .LBB0_514
	s_branch .LBB0_513

.LBB0_514:
	s_lshl_b32 s33, s18, 14
	ds_read_b128 v[170:173], v213 offset:40960
	ds_read_b128 v[174:177], v214 offset:40960
	ds_read_b128 v[178:181], v214 offset:32768
	ds_read_b128 v[182:185], v213 offset:32768
	s_andn2_b64 vcc, exec, s[4:5]
	s_add_i32 s31, s19, 1
	s_cbranch_vccnz .LBB0_516
	s_sub_u32 s35, s19, 63
	s_cmp_lt_u32 s19, 63
	s_cselect_b32 s100, s31, s35
	s_cselect_b32 s5, s17, s26
	s_cselect_b32 s4, s16, s25
	s_cselect_b32 s35, s24, s28
	s_cselect_b32 s34, s23, s27
	s_mul_i32 s101, s100, 0x30000
	s_add_u32 s4, s4, s101
	s_addc_u32 s5, s5, 0
	s_lshl_b32 s101, s100, 18
	s_add_u32 s34, s34, s101
	s_addc_u32 s35, s35, 0
	s_lshl_b32 s33, s18, 14
	s_xor_b32 s100, s33, 0x4000
	s_add_i32 s100, s29, s100
	s_add_i32 m0, s100, 0x8000
	s_nop 0
	global_load_lds_dwordx4 v208, s[4:5]
	s_mov_b32 m0, s100
	s_nop 0
	global_load_lds_dwordx4 v209, s[34:35]
	s_add_i32 m0, s100, 0xa000
	s_nop 0
	global_load_lds_dwordx4 v210, s[4:5]
	s_add_i32 m0, s100, 0x2000
	s_nop 0
	global_load_lds_dwordx4 v211, s[34:35]
	s_lshl_b32 s34, s18, 13
	s_xor_b32 s101, s34, 0x2000
	s_add_i32 m0, s30, s101
	s_nop 0
	global_load_lds_dwordx4 v212, s[4:5]
.LBB0_516:
	s_add_i32 s4, s33, 0
	s_add_i32 s5, s34, 0
	s_add_i32 s5, s5, 0x10000
	s_waitcnt lgkmcnt(2)
	v_mfma_f32_32x32x16_bf16 v[68:83], v[170:173], v[100:103], 0
	v_mfma_f32_32x32x16_bf16 v[68:83], v[174:177], v[104:107], v[68:83]
	ds_read_b128 v[170:173], v215 offset:32768
	ds_read_b128 v[174:177], v216 offset:32768
	s_waitcnt lgkmcnt(2)
	v_mfma_f32_32x32x16_bf16 v[84:99], v[178:181], v[104:107], 0
	v_mfma_f32_32x32x16_bf16 v[84:99], v[182:185], v[100:103], v[84:99]
	ds_read_b128 v[178:181], v216 offset:40960
	ds_read_b128 v[182:185], v215 offset:40960
	s_waitcnt lgkmcnt(2)
	v_mfma_f32_32x32x16_bf16 v[84:99], v[170:173], v[108:111], v[84:99]
	v_mfma_f32_32x32x16_bf16 v[84:99], v[174:177], v[112:115], v[84:99]
	ds_read_b128 v[170:173], v217 offset:40960
	ds_read_b128 v[174:177], v218 offset:40960
	s_waitcnt lgkmcnt(2)
	v_mfma_f32_32x32x16_bf16 v[68:83], v[178:181], v[112:115], v[68:83]
	v_mfma_f32_32x32x16_bf16 v[68:83], v[182:185], v[108:111], v[68:83]
	ds_read_b128 v[178:181], v218 offset:32768
	ds_read_b128 v[182:185], v217 offset:32768
	s_waitcnt lgkmcnt(2)
	v_mfma_f32_32x32x16_bf16 v[68:83], v[170:173], v[116:119], v[68:83]
	v_mfma_f32_32x32x16_bf16 v[68:83], v[174:177], v[120:123], v[68:83]
	ds_read_b128 v[170:173], v219 offset:32768
	ds_read_b128 v[174:177], v220 offset:32768
	s_waitcnt lgkmcnt(2)
	v_mfma_f32_32x32x16_bf16 v[84:99], v[178:181], v[120:123], v[84:99]
	v_mfma_f32_32x32x16_bf16 v[84:99], v[182:185], v[116:119], v[84:99]
	ds_read_b128 v[178:181], v220 offset:40960
	ds_read_b128 v[182:185], v219 offset:40960
	s_waitcnt lgkmcnt(2)
	v_mfma_f32_32x32x16_bf16 v[84:99], v[170:173], v[124:127], v[84:99]
	v_mfma_f32_32x32x16_bf16 v[84:99], v[174:177], v[128:131], v[84:99]
	ds_read_b128 v[170:173], v221 offset:4096
	ds_read_b128 v[174:177], v222 offset:4096
	s_waitcnt lgkmcnt(2)
	v_mfma_f32_32x32x16_bf16 v[68:83], v[178:181], v[128:131], v[68:83]
	v_mfma_f32_32x32x16_bf16 v[68:83], v[182:185], v[124:127], v[68:83]
	ds_read_b128 v[178:181], v222 offset:0
	ds_read_b128 v[182:185], v221 offset:0
	s_waitcnt lgkmcnt(2)
	v_mfma_f32_32x32x16_bf16 v[68:83], v[170:173], v[186:189], v[68:83]
	v_mfma_f32_32x32x16_bf16 v[68:83], v[174:177], v[190:193], v[68:83]
	ds_read_b128 v[170:173], v223 offset:0
	ds_read_b128 v[174:177], v224 offset:0
	s_waitcnt lgkmcnt(2)
	v_mfma_f32_32x32x16_bf16 v[84:99], v[178:181], v[190:193], v[84:99]
	v_mfma_f32_32x32x16_bf16 v[84:99], v[182:185], v[186:189], v[84:99]
	ds_read_b128 v[178:181], v224 offset:4096
	ds_read_b128 v[182:185], v223 offset:4096
	s_waitcnt lgkmcnt(2)
	v_mfma_f32_32x32x16_bf16 v[84:99], v[170:173], v[194:197], v[84:99]
	v_mfma_f32_32x32x16_bf16 v[84:99], v[174:177], v[204:207], v[84:99]
	s_mov_b32 s4, 0x42ddb3d8
	s_waitcnt lgkmcnt(0)
	v_mfma_f32_32x32x16_bf16 v[68:83], v[178:181], v[204:207], v[68:83]
	v_mfma_f32_32x32x16_bf16 v[68:83], v[182:185], v[194:197], v[68:83]
	s_nop 10
	v_max_f32_e32 v2, v84, v85
	v_max3_f32 v2, v2, v86, v87
	v_max3_f32 v2, v2, v88, v89
	v_max3_f32 v2, v2, v90, v91
	v_max3_f32 v2, v2, v92, v93
	v_max3_f32 v2, v2, v94, v95
	v_max3_f32 v2, v2, v96, v97
	v_max3_f32 v2, v2, v98, v99
	v_max3_f32 v2, v2, v68, v69
	v_max3_f32 v2, v2, v70, v71
	v_max3_f32 v2, v2, v72, v73
	v_max3_f32 v2, v2, v74, v75
	v_max3_f32 v2, v2, v76, v77
	v_max3_f32 v2, v2, v78, v79
	v_max3_f32 v2, v2, v80, v81
	v_max3_f32 v2, v2, v82, v83
	v_mov_b32_e32 v145, v2
	s_nop 1
	v_permlane32_swap_b32_e32 v2, v145
	v_max_f32_e32 v2, v2, v145
	v_sub_f32_e32 v145, v2, v167
	v_cmp_ge_f32_e32 vcc, s4, v145
	s_cmp_eq_u64 vcc, exec
	s_cbranch_scc0 .Lmla_resc_slow
	v_mov_b32_e32 v2, 1.0
	s_mov_b64 s[4:5], -1
.LBB0_520:
	v_cndmask_b32_e64 v167, v145, v167, s[4:5]
	v_mul_f32_e32 v145, 0xbdd53b94, v167
	v_fmamk_f32 v84, v84, 0x3dd53b94, v145
	v_fmamk_f32 v85, v85, 0x3dd53b94, v145
	v_fmamk_f32 v86, v86, 0x3dd53b94, v145
	v_fmamk_f32 v87, v87, 0x3dd53b94, v145
	v_fmamk_f32 v88, v88, 0x3dd53b94, v145
	v_fmamk_f32 v89, v89, 0x3dd53b94, v145
	v_fmamk_f32 v90, v90, 0x3dd53b94, v145
	v_fmamk_f32 v91, v91, 0x3dd53b94, v145
	v_fmamk_f32 v92, v92, 0x3dd53b94, v145
	v_fmamk_f32 v93, v93, 0x3dd53b94, v145
	v_fmamk_f32 v94, v94, 0x3dd53b94, v145
	v_fmamk_f32 v95, v95, 0x3dd53b94, v145
	v_fmamk_f32 v96, v96, 0x3dd53b94, v145
	v_fmamk_f32 v97, v97, 0x3dd53b94, v145
	v_fmamk_f32 v98, v98, 0x3dd53b94, v145
	v_fmamk_f32 v99, v99, 0x3dd53b94, v145
	v_fmamk_f32 v68, v68, 0x3dd53b94, v145
	v_fmamk_f32 v69, v69, 0x3dd53b94, v145
	v_fmamk_f32 v70, v70, 0x3dd53b94, v145
	v_fmamk_f32 v71, v71, 0x3dd53b94, v145
	v_fmamk_f32 v72, v72, 0x3dd53b94, v145
	v_fmamk_f32 v73, v73, 0x3dd53b94, v145
	v_fmamk_f32 v74, v74, 0x3dd53b94, v145
	v_fmamk_f32 v75, v75, 0x3dd53b94, v145
	v_fmamk_f32 v76, v76, 0x3dd53b94, v145
	v_fmamk_f32 v77, v77, 0x3dd53b94, v145
	v_fmamk_f32 v78, v78, 0x3dd53b94, v145
	v_fmamk_f32 v79, v79, 0x3dd53b94, v145
	v_fmamk_f32 v80, v80, 0x3dd53b94, v145
	v_fmamk_f32 v81, v81, 0x3dd53b94, v145
	v_fmamk_f32 v82, v82, 0x3dd53b94, v145
	v_fmac_f32_e32 v145, 0x3dd53b94, v83
	v_exp_f32_e32 v83, v84
	v_exp_f32_e32 v84, v85
	v_exp_f32_e32 v85, v86
	v_exp_f32_e32 v86, v87
	v_exp_f32_e32 v87, v88
	v_exp_f32_e32 v88, v89
	v_exp_f32_e32 v89, v90
	v_exp_f32_e32 v90, v91
	v_exp_f32_e32 v91, v92
	v_exp_f32_e32 v92, v93
	v_exp_f32_e32 v93, v94
	v_exp_f32_e32 v94, v95
	v_exp_f32_e32 v95, v96
	v_exp_f32_e32 v96, v97
	v_exp_f32_e32 v97, v98
	v_exp_f32_e32 v98, v99
	v_exp_f32_e32 v99, v68
	v_add_f32_e32 v68, 0, v83
	v_add_f32_e32 v68, v84, v68
	v_add_f32_e32 v68, v85, v68
	v_add_f32_e32 v68, v86, v68
	v_add_f32_e32 v68, v87, v68
	v_add_f32_e32 v68, v88, v68
	v_add_f32_e32 v68, v89, v68
	v_add_f32_e32 v68, v90, v68
	v_add_f32_e32 v68, v91, v68
	v_add_f32_e32 v68, v92, v68
	v_add_f32_e32 v68, v93, v68
	v_add_f32_e32 v68, v94, v68
	v_add_f32_e32 v68, v95, v68
	v_exp_f32_e32 v69, v69
	v_add_f32_e32 v68, v96, v68
	v_exp_f32_e32 v147, v70
	v_add_f32_e32 v68, v97, v68
	v_exp_f32_e32 v151, v71
	v_add_f32_e32 v68, v98, v68
	v_exp_f32_e32 v153, v72
	v_add_f32_e32 v68, v99, v68
	v_exp_f32_e32 v169, v73
	v_add_f32_e32 v68, v69, v68
	v_exp_f32_e32 v170, v74
	v_add_f32_e32 v68, v147, v68
	v_exp_f32_e32 v171, v75
	v_add_f32_e32 v68, v151, v68
	v_exp_f32_e32 v172, v76
	v_add_f32_e32 v68, v153, v68
	v_exp_f32_e32 v173, v77
	v_add_f32_e32 v68, v169, v68
	v_exp_f32_e32 v174, v78
	v_add_f32_e32 v68, v170, v68
	v_exp_f32_e32 v175, v79
	v_add_f32_e32 v68, v171, v68
	v_exp_f32_e32 v176, v80
	v_add_f32_e32 v68, v172, v68
	v_exp_f32_e32 v177, v81
	v_add_f32_e32 v68, v173, v68
	v_exp_f32_e32 v178, v82
	v_add_f32_e32 v68, v174, v68
	v_exp_f32_e32 v145, v145
	v_add_f32_e32 v68, v175, v68
	v_add_f32_e32 v68, v176, v68
	v_add_f32_e32 v68, v177, v68
	v_add_f32_e32 v68, v178, v68
	v_add_f32_e32 v68, v145, v68
	v_mov_b32_e32 v70, v68
	s_nop 1
	v_permlane32_swap_b32_e32 v68, v70
	v_add_f32_e32 v68, v68, v70
	v_fmac_f32_e32 v68, v168, v2
	v_cvt_pk_bf16_f32 v70, v83, v84
	v_cvt_pk_bf16_f32 v71, v85, v86
	v_cvt_pk_bf16_f32 v72, v87, v88
	v_cvt_pk_bf16_f32 v73, v89, v90
	v_cvt_pk_bf16_f32 v74, v91, v92
	v_cvt_pk_bf16_f32 v75, v93, v94
	v_cvt_pk_bf16_f32 v76, v95, v96
	v_cvt_pk_bf16_f32 v77, v97, v98
	v_cvt_pk_bf16_f32 v78, v99, v69
	v_cvt_pk_bf16_f32 v79, v147, v151
	v_cvt_pk_bf16_f32 v80, v153, v169
	v_cvt_pk_bf16_f32 v81, v170, v171
	v_cvt_pk_bf16_f32 v82, v172, v173
	v_cvt_pk_bf16_f32 v83, v174, v175
	v_cvt_pk_bf16_f32 v84, v176, v177
	v_cvt_pk_bf16_f32 v85, v178, v145
	v_permlane32_swap_b32_e32 v70, v72
	v_permlane32_swap_b32_e32 v71, v73
	v_permlane32_swap_b32_e32 v74, v76
	v_permlane32_swap_b32_e32 v75, v77
	v_permlane32_swap_b32_e32 v78, v80
	v_permlane32_swap_b32_e32 v79, v81
	v_permlane32_swap_b32_e32 v82, v84
	v_permlane32_swap_b32_e32 v83, v85
	ds_read_b64_tr_b16 v[86:87], v166 offset:0
	ds_read_b64_tr_b16 v[88:89], v166 offset:2048
	ds_read_b64_tr_b16 v[90:91], v166 offset:4096
	ds_read_b64_tr_b16 v[92:93], v166 offset:6144
	ds_read_b64_tr_b16 v[94:95], v166 offset:8192
	ds_read_b64_tr_b16 v[96:97], v166 offset:10240
	ds_read_b64_tr_b16 v[168:169], v166 offset:12288
	ds_read_b64_tr_b16 v[170:171], v166 offset:14336
	s_waitcnt lgkmcnt(6)
	s_nop 0
	v_mfma_f32_32x32x16_bf16 v[52:67], v[70:73], v[86:89], v[52:67]
	ds_read_b64_tr_b16 v[86:87], v166 offset:512
	ds_read_b64_tr_b16 v[88:89], v166 offset:2560
	s_waitcnt lgkmcnt(6)
	v_mfma_f32_32x32x16_bf16 v[52:67], v[74:77], v[90:93], v[52:67]
	ds_read_b64_tr_b16 v[90:91], v166 offset:4608
	ds_read_b64_tr_b16 v[92:93], v166 offset:6656
	s_waitcnt lgkmcnt(6)
	v_mfma_f32_32x32x16_bf16 v[52:67], v[78:81], v[94:97], v[52:67]
	ds_read_b64_tr_b16 v[94:95], v166 offset:8704
	ds_read_b64_tr_b16 v[96:97], v166 offset:10752
	s_waitcnt lgkmcnt(6)
	v_mfma_f32_32x32x16_bf16 v[52:67], v[82:85], v[168:171], v[52:67]
	ds_read_b64_tr_b16 v[168:169], v166 offset:12800
	ds_read_b64_tr_b16 v[170:171], v166 offset:14848
	s_waitcnt lgkmcnt(6)
	v_mfma_f32_32x32x16_bf16 v[36:51], v[70:73], v[86:89], v[36:51]
	ds_read_b64_tr_b16 v[86:87], v166 offset:1024
	ds_read_b64_tr_b16 v[88:89], v166 offset:3072
	s_waitcnt lgkmcnt(6)
	v_mfma_f32_32x32x16_bf16 v[36:51], v[74:77], v[90:93], v[36:51]
	ds_read_b64_tr_b16 v[90:91], v166 offset:5120
	ds_read_b64_tr_b16 v[92:93], v166 offset:7168
	s_waitcnt lgkmcnt(6)
	v_mfma_f32_32x32x16_bf16 v[36:51], v[78:81], v[94:97], v[36:51]
	ds_read_b64_tr_b16 v[94:95], v166 offset:9216
	ds_read_b64_tr_b16 v[96:97], v166 offset:11264
	s_waitcnt lgkmcnt(6)
	v_mfma_f32_32x32x16_bf16 v[36:51], v[82:85], v[168:171], v[36:51]
	ds_read_b64_tr_b16 v[168:169], v166 offset:13312
	ds_read_b64_tr_b16 v[170:171], v166 offset:15360
	s_waitcnt lgkmcnt(6)
	v_mfma_f32_32x32x16_bf16 v[20:35], v[70:73], v[86:89], v[20:35]
	ds_read_b64_tr_b16 v[86:87], v166 offset:1536
	ds_read_b64_tr_b16 v[88:89], v166 offset:3584
	s_waitcnt lgkmcnt(6)
	v_mfma_f32_32x32x16_bf16 v[20:35], v[74:77], v[90:93], v[20:35]
	ds_read_b64_tr_b16 v[90:91], v166 offset:5632
	ds_read_b64_tr_b16 v[92:93], v166 offset:7680
	s_waitcnt lgkmcnt(6)
	v_mfma_f32_32x32x16_bf16 v[20:35], v[78:81], v[94:97], v[20:35]
	ds_read_b64_tr_b16 v[94:95], v166 offset:9728
	ds_read_b64_tr_b16 v[96:97], v166 offset:11776
	s_waitcnt lgkmcnt(6)
	v_mfma_f32_32x32x16_bf16 v[20:35], v[82:85], v[168:171], v[20:35]
	ds_read_b64_tr_b16 v[168:169], v166 offset:13824
	ds_read_b64_tr_b16 v[170:171], v166 offset:15872
	s_waitcnt vmcnt(0) lgkmcnt(0)
	s_cmpk_eq_i32 s31, 0x48
	s_waitcnt vmcnt(0)
	s_barrier
	v_mfma_f32_32x32x16_bf16 v[4:19], v[70:73], v[86:89], v[4:19]
	v_mfma_f32_32x32x16_bf16 v[4:19], v[74:77], v[90:93], v[4:19]
	v_mfma_f32_32x32x16_bf16 v[4:19], v[78:81], v[94:97], v[4:19]
	v_mfma_f32_32x32x16_bf16 v[4:19], v[82:85], v[168:171], v[4:19]
	s_cbranch_scc0 .LBB0_512b
	s_and_saveexec_b64 s[4:5], s[0:1]
	s_cbranch_execz .LBB0_497
	ds_write_b32 v159, v68
	s_branch .LBB0_497
.Lmla_resc_slow:
	v_max_f32_e32 v145, v167, v2
	v_sub_f32_e32 v2, v167, v145
	v_mul_f32_e32 v2, 0x3dd53b94, v2
	v_exp_f32_e32 v2, v2
	s_mov_b64 s[4:5], 0
	s_nop 0
	v_cmp_gt_f32_e32 vcc, 1.0, v2
	s_cbranch_vccz .LBB0_520
	s_and_saveexec_b64 s[18:19], s[0:1]
	ds_write_b32 v159, v2 offset:128
	s_or_b64 exec, exec, s[18:19]
	s_waitcnt lgkmcnt(0)
	ds_read_b128 v[170:173], v154 offset:224
	ds_read_b128 v[174:177], v154 offset:192
	ds_read_b128 v[178:181], v154 offset:160
	ds_read_b128 v[182:185], v154 offset:128
	s_waitcnt lgkmcnt(0)
	v_pk_mul_f32 v[66:67], v[66:67], v[172:173]
	v_pk_mul_f32 v[62:63], v[62:63], v[176:177]
	v_pk_mul_f32 v[58:59], v[58:59], v[180:181]
	v_pk_mul_f32 v[54:55], v[54:55], v[184:185]
	v_pk_mul_f32 v[64:65], v[64:65], v[170:171]
	v_pk_mul_f32 v[60:61], v[60:61], v[174:175]
	v_pk_mul_f32 v[56:57], v[56:57], v[178:179]
	v_pk_mul_f32 v[52:53], v[52:53], v[182:183]
	v_pk_mul_f32 v[50:51], v[50:51], v[172:173]
	v_pk_mul_f32 v[46:47], v[46:47], v[176:177]
	v_pk_mul_f32 v[42:43], v[42:43], v[180:181]
	v_pk_mul_f32 v[38:39], v[38:39], v[184:185]
	v_pk_mul_f32 v[48:49], v[48:49], v[170:171]
	v_pk_mul_f32 v[44:45], v[44:45], v[174:175]
	v_pk_mul_f32 v[40:41], v[40:41], v[178:179]
	v_pk_mul_f32 v[36:37], v[36:37], v[182:183]
	v_pk_mul_f32 v[34:35], v[34:35], v[172:173]
	v_pk_mul_f32 v[30:31], v[30:31], v[176:177]
	v_pk_mul_f32 v[26:27], v[26:27], v[180:181]
	v_pk_mul_f32 v[22:23], v[22:23], v[184:185]
	v_pk_mul_f32 v[32:33], v[32:33], v[170:171]
	v_pk_mul_f32 v[28:29], v[28:29], v[174:175]
	v_pk_mul_f32 v[24:25], v[24:25], v[178:179]
	v_pk_mul_f32 v[20:21], v[20:21], v[182:183]
	v_pk_mul_f32 v[18:19], v[18:19], v[172:173]
	v_pk_mul_f32 v[14:15], v[14:15], v[176:177]
	v_pk_mul_f32 v[10:11], v[10:11], v[180:181]
	v_pk_mul_f32 v[6:7], v[6:7], v[184:185]
	v_pk_mul_f32 v[16:17], v[16:17], v[170:171]
	v_pk_mul_f32 v[12:13], v[12:13], v[174:175]
	v_pk_mul_f32 v[8:9], v[8:9], v[178:179]
	v_pk_mul_f32 v[4:5], v[4:5], v[182:183]
	s_branch .LBB0_520
.LBB0_512b:
	s_mov_b32 s19, s31
	v_mov_b32_e32 v168, v68
	s_and_b32 s18, s19, 1
	s_cmpk_lt_u32 s19, 0x47
	s_mov_b64 s[4:5], -1
	s_cbranch_scc1 .LBB0_514b

.LBB0_514b:
	s_lshl_b32 s33, s18, 14
	ds_read_b128 v[170:173], v213 offset:57344
	ds_read_b128 v[174:177], v214 offset:57344
	ds_read_b128 v[178:181], v214 offset:49152
	ds_read_b128 v[182:185], v213 offset:49152
	s_andn2_b64 vcc, exec, s[4:5]
	s_add_i32 s31, s19, 1
	s_cbranch_vccnz .LBB0_516b
	s_sub_u32 s35, s19, 63
	s_cmp_lt_u32 s19, 63
	s_cselect_b32 s100, s31, s35
	s_cselect_b32 s5, s17, s26
	s_cselect_b32 s4, s16, s25
	s_cselect_b32 s35, s24, s28
	s_cselect_b32 s34, s23, s27
	s_mul_i32 s101, s100, 0x30000
	s_add_u32 s4, s4, s101
	s_addc_u32 s5, s5, 0
	s_lshl_b32 s101, s100, 18
	s_add_u32 s34, s34, s101
	s_addc_u32 s35, s35, 0
	s_lshl_b32 s33, s18, 14
	s_xor_b32 s100, s33, 0x4000
	s_add_i32 s100, s29, s100
	s_add_i32 m0, s100, 0x8000
	s_nop 0
	global_load_lds_dwordx4 v208, s[4:5]
	s_mov_b32 m0, s100
	s_nop 0
	global_load_lds_dwordx4 v209, s[34:35]
	s_add_i32 m0, s100, 0xa000
	s_nop 0
	global_load_lds_dwordx4 v210, s[4:5]
	s_add_i32 m0, s100, 0x2000
	s_nop 0
	global_load_lds_dwordx4 v211, s[34:35]
	s_lshl_b32 s34, s18, 13
	s_xor_b32 s101, s34, 0x2000
	s_add_i32 m0, s30, s101
	s_nop 0
	global_load_lds_dwordx4 v212, s[4:5]
.LBB0_516b:
	s_add_i32 s4, s33, 0
	s_add_i32 s5, s34, 0
	s_add_i32 s5, s5, 0x10000
	s_waitcnt lgkmcnt(2)
	v_mfma_f32_32x32x16_bf16 v[68:83], v[170:173], v[100:103], 0
	v_mfma_f32_32x32x16_bf16 v[68:83], v[174:177], v[104:107], v[68:83]
	ds_read_b128 v[170:173], v215 offset:49152
	ds_read_b128 v[174:177], v216 offset:49152
	s_waitcnt lgkmcnt(2)
	v_mfma_f32_32x32x16_bf16 v[84:99], v[178:181], v[104:107], 0
	v_mfma_f32_32x32x16_bf16 v[84:99], v[182:185], v[100:103], v[84:99]
	ds_read_b128 v[178:181], v216 offset:57344
	ds_read_b128 v[182:185], v215 offset:57344
	s_waitcnt lgkmcnt(2)
	v_mfma_f32_32x32x16_bf16 v[84:99], v[170:173], v[108:111], v[84:99]
	v_mfma_f32_32x32x16_bf16 v[84:99], v[174:177], v[112:115], v[84:99]
	ds_read_b128 v[170:173], v217 offset:57344
	ds_read_b128 v[174:177], v218 offset:57344
	s_waitcnt lgkmcnt(2)
	v_mfma_f32_32x32x16_bf16 v[68:83], v[178:181], v[112:115], v[68:83]
	v_mfma_f32_32x32x16_bf16 v[68:83], v[182:185], v[108:111], v[68:83]
	ds_read_b128 v[178:181], v218 offset:49152
	ds_read_b128 v[182:185], v217 offset:49152
	s_waitcnt lgkmcnt(2)
	v_mfma_f32_32x32x16_bf16 v[68:83], v[170:173], v[116:119], v[68:83]
	v_mfma_f32_32x32x16_bf16 v[68:83], v[174:177], v[120:123], v[68:83]
	ds_read_b128 v[170:173], v219 offset:49152
	ds_read_b128 v[174:177], v220 offset:49152
	s_waitcnt lgkmcnt(2)
	v_mfma_f32_32x32x16_bf16 v[84:99], v[178:181], v[120:123], v[84:99]
	v_mfma_f32_32x32x16_bf16 v[84:99], v[182:185], v[116:119], v[84:99]
	ds_read_b128 v[178:181], v220 offset:57344
	ds_read_b128 v[182:185], v219 offset:57344
	s_waitcnt lgkmcnt(2)
	v_mfma_f32_32x32x16_bf16 v[84:99], v[170:173], v[124:127], v[84:99]
	v_mfma_f32_32x32x16_bf16 v[84:99], v[174:177], v[128:131], v[84:99]
	ds_read_b128 v[170:173], v221 offset:12288
	ds_read_b128 v[174:177], v222 offset:12288
	s_waitcnt lgkmcnt(2)
	v_mfma_f32_32x32x16_bf16 v[68:83], v[178:181], v[128:131], v[68:83]
	v_mfma_f32_32x32x16_bf16 v[68:83], v[182:185], v[124:127], v[68:83]
	ds_read_b128 v[178:181], v222 offset:8192
	ds_read_b128 v[182:185], v221 offset:8192
	s_waitcnt lgkmcnt(2)
	v_mfma_f32_32x32x16_bf16 v[68:83], v[170:173], v[186:189], v[68:83]
	v_mfma_f32_32x32x16_bf16 v[68:83], v[174:177], v[190:193], v[68:83]
	ds_read_b128 v[170:173], v223 offset:8192
	ds_read_b128 v[174:177], v224 offset:8192
	s_waitcnt lgkmcnt(2)
	v_mfma_f32_32x32x16_bf16 v[84:99], v[178:181], v[190:193], v[84:99]
	v_mfma_f32_32x32x16_bf16 v[84:99], v[182:185], v[186:189], v[84:99]
	ds_read_b128 v[178:181], v224 offset:12288
	ds_read_b128 v[182:185], v223 offset:12288
	s_waitcnt lgkmcnt(2)
	v_mfma_f32_32x32x16_bf16 v[84:99], v[170:173], v[194:197], v[84:99]
	v_mfma_f32_32x32x16_bf16 v[84:99], v[174:177], v[204:207], v[84:99]
	s_mov_b32 s4, 0x42ddb3d8
	s_waitcnt lgkmcnt(0)
	v_mfma_f32_32x32x16_bf16 v[68:83], v[178:181], v[204:207], v[68:83]
	v_mfma_f32_32x32x16_bf16 v[68:83], v[182:185], v[194:197], v[68:83]
	s_nop 10
	v_max_f32_e32 v2, v84, v85
	v_max3_f32 v2, v2, v86, v87
	v_max3_f32 v2, v2, v88, v89
	v_max3_f32 v2, v2, v90, v91
	v_max3_f32 v2, v2, v92, v93
	v_max3_f32 v2, v2, v94, v95
	v_max3_f32 v2, v2, v96, v97
	v_max3_f32 v2, v2, v98, v99
	v_max3_f32 v2, v2, v68, v69
	v_max3_f32 v2, v2, v70, v71
	v_max3_f32 v2, v2, v72, v73
	v_max3_f32 v2, v2, v74, v75
	v_max3_f32 v2, v2, v76, v77
	v_max3_f32 v2, v2, v78, v79
	v_max3_f32 v2, v2, v80, v81
	v_max3_f32 v2, v2, v82, v83
	v_mov_b32_e32 v145, v2
	s_nop 1
	v_permlane32_swap_b32_e32 v2, v145
	v_max_f32_e32 v2, v2, v145
	v_sub_f32_e32 v145, v2, v167
	v_cmp_ge_f32_e32 vcc, s4, v145
	s_cmp_eq_u64 vcc, exec
	s_cbranch_scc0 .Lmla_resc_slowb
	v_mov_b32_e32 v2, 1.0
	s_mov_b64 s[4:5], -1
.LBB0_520b:
	v_cndmask_b32_e64 v167, v145, v167, s[4:5]
	v_mul_f32_e32 v145, 0xbdd53b94, v167
	v_fmamk_f32 v84, v84, 0x3dd53b94, v145
	v_fmamk_f32 v85, v85, 0x3dd53b94, v145
	v_fmamk_f32 v86, v86, 0x3dd53b94, v145
	v_fmamk_f32 v87, v87, 0x3dd53b94, v145
	v_fmamk_f32 v88, v88, 0x3dd53b94, v145
	v_fmamk_f32 v89, v89, 0x3dd53b94, v145
	v_fmamk_f32 v90, v90, 0x3dd53b94, v145
	v_fmamk_f32 v91, v91, 0x3dd53b94, v145
	v_fmamk_f32 v92, v92, 0x3dd53b94, v145
	v_fmamk_f32 v93, v93, 0x3dd53b94, v145
	v_fmamk_f32 v94, v94, 0x3dd53b94, v145
	v_fmamk_f32 v95, v95, 0x3dd53b94, v145
	v_fmamk_f32 v96, v96, 0x3dd53b94, v145
	v_fmamk_f32 v97, v97, 0x3dd53b94, v145
	v_fmamk_f32 v98, v98, 0x3dd53b94, v145
	v_fmamk_f32 v99, v99, 0x3dd53b94, v145
	v_fmamk_f32 v68, v68, 0x3dd53b94, v145
	v_fmamk_f32 v69, v69, 0x3dd53b94, v145
	v_fmamk_f32 v70, v70, 0x3dd53b94, v145
	v_fmamk_f32 v71, v71, 0x3dd53b94, v145
	v_fmamk_f32 v72, v72, 0x3dd53b94, v145
	v_fmamk_f32 v73, v73, 0x3dd53b94, v145
	v_fmamk_f32 v74, v74, 0x3dd53b94, v145
	v_fmamk_f32 v75, v75, 0x3dd53b94, v145
	v_fmamk_f32 v76, v76, 0x3dd53b94, v145
	v_fmamk_f32 v77, v77, 0x3dd53b94, v145
	v_fmamk_f32 v78, v78, 0x3dd53b94, v145
	v_fmamk_f32 v79, v79, 0x3dd53b94, v145
	v_fmamk_f32 v80, v80, 0x3dd53b94, v145
	v_fmamk_f32 v81, v81, 0x3dd53b94, v145
	v_fmamk_f32 v82, v82, 0x3dd53b94, v145
	v_fmac_f32_e32 v145, 0x3dd53b94, v83
	v_exp_f32_e32 v83, v84
	v_exp_f32_e32 v84, v85
	v_exp_f32_e32 v85, v86
	v_exp_f32_e32 v86, v87
	v_exp_f32_e32 v87, v88
	v_exp_f32_e32 v88, v89
	v_exp_f32_e32 v89, v90
	v_exp_f32_e32 v90, v91
	v_exp_f32_e32 v91, v92
	v_exp_f32_e32 v92, v93
	v_exp_f32_e32 v93, v94
	v_exp_f32_e32 v94, v95
	v_exp_f32_e32 v95, v96
	v_exp_f32_e32 v96, v97
	v_exp_f32_e32 v97, v98
	v_exp_f32_e32 v98, v99
	v_exp_f32_e32 v99, v68
	v_add_f32_e32 v68, 0, v83
	v_add_f32_e32 v68, v84, v68
	v_add_f32_e32 v68, v85, v68
	v_add_f32_e32 v68, v86, v68
	v_add_f32_e32 v68, v87, v68
	v_add_f32_e32 v68, v88, v68
	v_add_f32_e32 v68, v89, v68
	v_add_f32_e32 v68, v90, v68
	v_add_f32_e32 v68, v91, v68
	v_add_f32_e32 v68, v92, v68
	v_add_f32_e32 v68, v93, v68
	v_add_f32_e32 v68, v94, v68
	v_add_f32_e32 v68, v95, v68
	v_exp_f32_e32 v69, v69
	v_add_f32_e32 v68, v96, v68
	v_exp_f32_e32 v147, v70
	v_add_f32_e32 v68, v97, v68
	v_exp_f32_e32 v151, v71
	v_add_f32_e32 v68, v98, v68
	v_exp_f32_e32 v153, v72
	v_add_f32_e32 v68, v99, v68
	v_exp_f32_e32 v169, v73
	v_add_f32_e32 v68, v69, v68
	v_exp_f32_e32 v170, v74
	v_add_f32_e32 v68, v147, v68
	v_exp_f32_e32 v171, v75
	v_add_f32_e32 v68, v151, v68
	v_exp_f32_e32 v172, v76
	v_add_f32_e32 v68, v153, v68
	v_exp_f32_e32 v173, v77
	v_add_f32_e32 v68, v169, v68
	v_exp_f32_e32 v174, v78
	v_add_f32_e32 v68, v170, v68
	v_exp_f32_e32 v175, v79
	v_add_f32_e32 v68, v171, v68
	v_exp_f32_e32 v176, v80
	v_add_f32_e32 v68, v172, v68
	v_exp_f32_e32 v177, v81
	v_add_f32_e32 v68, v173, v68
	v_exp_f32_e32 v178, v82
	v_add_f32_e32 v68, v174, v68
	v_exp_f32_e32 v145, v145
	v_add_f32_e32 v68, v175, v68
	v_add_f32_e32 v68, v176, v68
	v_add_f32_e32 v68, v177, v68
	v_add_f32_e32 v68, v178, v68
	v_add_f32_e32 v68, v145, v68
	v_mov_b32_e32 v70, v68
	s_nop 1
	v_permlane32_swap_b32_e32 v68, v70
	v_add_f32_e32 v68, v68, v70
	v_fmac_f32_e32 v68, v168, v2
	v_cvt_pk_bf16_f32 v70, v83, v84
	v_cvt_pk_bf16_f32 v71, v85, v86
	v_cvt_pk_bf16_f32 v72, v87, v88
	v_cvt_pk_bf16_f32 v73, v89, v90
	v_cvt_pk_bf16_f32 v74, v91, v92
	v_cvt_pk_bf16_f32 v75, v93, v94
	v_cvt_pk_bf16_f32 v76, v95, v96
	v_cvt_pk_bf16_f32 v77, v97, v98
	v_cvt_pk_bf16_f32 v78, v99, v69
	v_cvt_pk_bf16_f32 v79, v147, v151
	v_cvt_pk_bf16_f32 v80, v153, v169
	v_cvt_pk_bf16_f32 v81, v170, v171
	v_cvt_pk_bf16_f32 v82, v172, v173
	v_cvt_pk_bf16_f32 v83, v174, v175
	v_cvt_pk_bf16_f32 v84, v176, v177
	v_cvt_pk_bf16_f32 v85, v178, v145
	v_permlane32_swap_b32_e32 v70, v72
	v_permlane32_swap_b32_e32 v71, v73
	v_permlane32_swap_b32_e32 v74, v76
	v_permlane32_swap_b32_e32 v75, v77
	v_permlane32_swap_b32_e32 v78, v80
	v_permlane32_swap_b32_e32 v79, v81
	v_permlane32_swap_b32_e32 v82, v84
	v_permlane32_swap_b32_e32 v83, v85
	ds_read_b64_tr_b16 v[86:87], v166 offset:16384
	ds_read_b64_tr_b16 v[88:89], v166 offset:18432
	ds_read_b64_tr_b16 v[90:91], v166 offset:20480
	ds_read_b64_tr_b16 v[92:93], v166 offset:22528
	ds_read_b64_tr_b16 v[94:95], v166 offset:24576
	ds_read_b64_tr_b16 v[96:97], v166 offset:26624
	ds_read_b64_tr_b16 v[168:169], v166 offset:28672
	ds_read_b64_tr_b16 v[170:171], v166 offset:30720
	s_waitcnt lgkmcnt(6)
	s_nop 0
	v_mfma_f32_32x32x16_bf16 v[52:67], v[70:73], v[86:89], v[52:67]
	ds_read_b64_tr_b16 v[86:87], v166 offset:16896
	ds_read_b64_tr_b16 v[88:89], v166 offset:18944
	s_waitcnt lgkmcnt(6)
	v_mfma_f32_32x32x16_bf16 v[52:67], v[74:77], v[90:93], v[52:67]
	ds_read_b64_tr_b16 v[90:91], v166 offset:20992
	ds_read_b64_tr_b16 v[92:93], v166 offset:23040
	s_waitcnt lgkmcnt(6)
	v_mfma_f32_32x32x16_bf16 v[52:67], v[78:81], v[94:97], v[52:67]
	ds_read_b64_tr_b16 v[94:95], v166 offset:25088
	ds_read_b64_tr_b16 v[96:97], v166 offset:27136
	s_waitcnt lgkmcnt(6)
	v_mfma_f32_32x32x16_bf16 v[52:67], v[82:85], v[168:171], v[52:67]
	ds_read_b64_tr_b16 v[168:169], v166 offset:29184
	ds_read_b64_tr_b16 v[170:171], v166 offset:31232
	s_waitcnt lgkmcnt(6)
	v_mfma_f32_32x32x16_bf16 v[36:51], v[70:73], v[86:89], v[36:51]
	ds_read_b64_tr_b16 v[86:87], v166 offset:17408
	ds_read_b64_tr_b16 v[88:89], v166 offset:19456
	s_waitcnt lgkmcnt(6)
	v_mfma_f32_32x32x16_bf16 v[36:51], v[74:77], v[90:93], v[36:51]
	ds_read_b64_tr_b16 v[90:91], v166 offset:21504
	ds_read_b64_tr_b16 v[92:93], v166 offset:23552
	s_waitcnt lgkmcnt(6)
	v_mfma_f32_32x32x16_bf16 v[36:51], v[78:81], v[94:97], v[36:51]
	ds_read_b64_tr_b16 v[94:95], v166 offset:25600
	ds_read_b64_tr_b16 v[96:97], v166 offset:27648
	s_waitcnt lgkmcnt(6)
	v_mfma_f32_32x32x16_bf16 v[36:51], v[82:85], v[168:171], v[36:51]
	ds_read_b64_tr_b16 v[168:169], v166 offset:29696
	ds_read_b64_tr_b16 v[170:171], v166 offset:31744
	s_waitcnt lgkmcnt(6)
	v_mfma_f32_32x32x16_bf16 v[20:35], v[70:73], v[86:89], v[20:35]
	ds_read_b64_tr_b16 v[86:87], v166 offset:17920
	ds_read_b64_tr_b16 v[88:89], v166 offset:19968
	s_waitcnt lgkmcnt(6)
	v_mfma_f32_32x32x16_bf16 v[20:35], v[74:77], v[90:93], v[20:35]
	ds_read_b64_tr_b16 v[90:91], v166 offset:22016
	ds_read_b64_tr_b16 v[92:93], v166 offset:24064
	s_waitcnt lgkmcnt(6)
	v_mfma_f32_32x32x16_bf16 v[20:35], v[78:81], v[94:97], v[20:35]
	ds_read_b64_tr_b16 v[94:95], v166 offset:26112
	ds_read_b64_tr_b16 v[96:97], v166 offset:28160
	s_waitcnt lgkmcnt(6)
	v_mfma_f32_32x32x16_bf16 v[20:35], v[82:85], v[168:171], v[20:35]
	ds_read_b64_tr_b16 v[168:169], v166 offset:30208
	ds_read_b64_tr_b16 v[170:171], v166 offset:32256
	s_waitcnt vmcnt(0) lgkmcnt(0)
	s_cmpk_eq_i32 s31, 0x48
	s_waitcnt vmcnt(0)
	s_barrier
	v_mfma_f32_32x32x16_bf16 v[4:19], v[70:73], v[86:89], v[4:19]
	v_mfma_f32_32x32x16_bf16 v[4:19], v[74:77], v[90:93], v[4:19]
	v_mfma_f32_32x32x16_bf16 v[4:19], v[78:81], v[94:97], v[4:19]
	v_mfma_f32_32x32x16_bf16 v[4:19], v[82:85], v[168:171], v[4:19]
	s_cbranch_scc0 .LBB0_512
	s_and_saveexec_b64 s[4:5], s[0:1]
	s_cbranch_execz .LBB0_497
	ds_write_b32 v159, v68
	s_branch .LBB0_497
